# v080 + final norm output stores sc1 nt (write-through)
# baseline (speedup 1.0000x reference)
.LBB0_1704:
	s_waitcnt vmcnt(8)
	v_lshlrev_b32_e32 v51, 16, v41
	v_lshlrev_b32_e32 v50, 16, v40
	v_and_b32_e32 v41, 0xffff0000, v41
	v_and_b32_e32 v40, 0xffff0000, v40
	v_lshlrev_b32_e32 v55, 16, v39
	v_lshlrev_b32_e32 v54, 16, v38
	v_and_b32_e32 v39, 0xffff0000, v39
	v_and_b32_e32 v38, 0xffff0000, v38
	v_pk_mul_f32 v[52:53], v[40:41], v[40:41]
	v_pk_mul_f32 v[56:57], v[38:39], v[38:39]
	v_lshlrev_b32_e32 v58, 16, v36
	v_and_b32_e32 v59, 0xffff0000, v36
	v_lshlrev_b32_e32 v64, 16, v37
	v_lshlrev_b32_e32 v60, 16, v34
	v_pk_fma_f32 v[52:53], v[50:51], v[50:51], v[52:53]
	v_pk_fma_f32 v[56:57], v[54:55], v[54:55], v[56:57]
	v_mul_f32_e32 v61, v58, v58
	v_mul_f32_e32 v63, v59, v59
	v_and_b32_e32 v65, 0xffff0000, v37
	v_mul_f32_e32 v36, v64, v64
	v_mov_b32_e32 v62, v60
	v_pk_add_f32 v[52:53], v[52:53], v[52:53] op_sel_hi:[0,1]
	v_pk_add_f32 v[56:57], v[56:57], v[56:57] op_sel_hi:[0,1]
	v_pk_fma_f32 v[36:37], v[64:65], v[64:65], v[36:37] op_sel_hi:[1,1,0]
	v_and_b32_e32 v68, 0xffff0000, v34
	v_lshlrev_b32_e32 v66, 16, v35
	v_and_b32_e32 v67, 0xffff0000, v35
	v_pk_add_f32 v[62:63], v[60:61], v[62:63]
	v_mul_f32_e32 v36, v68, v68
	v_mul_f32_e32 v56, v66, v66
	v_mul_f32_e32 v52, v67, v67
	v_mul_f32_e32 v34, v60, v60
	v_mov_b32_e32 v35, v63
	v_pk_add_f32 v[34:35], v[34:35], v[36:37]
	v_pk_add_f32 v[36:37], v[56:57], v[52:53]
	s_add_i32 s6, s9, s8
	v_pk_add_f32 v[52:53], v[34:35], v[36:37]
	v_add_f32_e32 v52, v52, v53
	s_nop 1
	v_mov_b32_dpp v53, v52 quad_perm:[1,0,3,2] row_mask:0xf bank_mask:0xf
	s_cmpk_gt_i32 s6, 0x3fff
	s_waitcnt lgkmcnt(0)
	v_add_f32_e32 v52, v52, v53
	s_nop 1
	v_mov_b32_dpp v53, v52 quad_perm:[2,3,0,1] row_mask:0xf bank_mask:0xf
	s_waitcnt lgkmcnt(0)
	v_add_f32_e32 v52, v52, v53
	s_nop 1
	v_mov_b32_dpp v53, v52 row_half_mirror row_mask:0xf bank_mask:0xf
	s_waitcnt lgkmcnt(0)
	v_add_f32_e32 v52, v52, v53
	s_nop 1
	v_mov_b32_dpp v53, v52 row_mirror row_mask:0xf bank_mask:0xf
	s_waitcnt lgkmcnt(0)
	v_add_f32_e32 v52, v52, v53
	v_mov_b32_e32 v53, v52
	s_nop 1
	v_permlane16_swap_b32_e32 v52, v53
	s_waitcnt lgkmcnt(0)
	v_add_f32_e32 v52, v52, v53
	v_mov_b32_e32 v53, v52
	s_nop 1
	v_permlane32_swap_b32_e32 v52, v53
	s_waitcnt lgkmcnt(0)
	v_add_f32_e32 v52, v52, v53
	v_fmamk_f32 v52, v52, 0x3a800000, v48
	v_mul_f32_e32 v53, 0x4f800000, v52
	v_cmp_gt_f32_e32 vcc, s12, v52
	s_nop 1
	v_cndmask_b32_e32 v52, v52, v53, vcc
	v_sqrt_f32_e32 v53, v52
	s_nop 0
	v_add_u32_e32 v56, -1, v53
	v_fma_f32 v57, -v56, v53, v52
	v_cmp_ge_f32_e64 s[0:1], 0, v57
	v_add_u32_e32 v57, 1, v53
	s_nop 0
	v_cndmask_b32_e64 v56, v53, v56, s[0:1]
	v_fma_f32 v53, -v57, v53, v52
	v_cmp_lt_f32_e64 s[0:1], 0, v53
	s_nop 1
	v_cndmask_b32_e64 v53, v56, v57, s[0:1]
	v_mul_f32_e32 v56, 0x37800000, v53
	v_cndmask_b32_e32 v53, v53, v56, vcc
	v_cmp_class_f32_e32 vcc, v52, v49
	s_nop 1
	v_cndmask_b32_e32 v52, v53, v52, vcc
	v_div_scale_f32 v53, s[0:1], v52, v52, 1.0
	v_rcp_f32_e32 v56, v53
	s_nop 0
	v_fma_f32 v57, -v53, v56, 1.0
	v_fmac_f32_e32 v56, v57, v56
	v_div_scale_f32 v57, vcc, 1.0, v52, 1.0
	v_mul_f32_e32 v61, v57, v56
	v_fma_f32 v62, -v53, v61, v57
	v_fmac_f32_e32 v61, v62, v56
	v_fma_f32 v53, -v53, v61, v57
	v_div_fmas_f32 v53, v53, v56, v61
	v_div_fixup_f32 v52, v53, v52, 1.0
	v_mov_b32_e32 v56, v50
	v_mov_b32_e32 v57, v40
	v_mov_b32_e32 v40, v51
	v_pk_mul_f32 v[56:57], v[52:53], v[56:57] op_sel_hi:[0,1]
	v_pk_mul_f32 v[40:41], v[52:53], v[40:41] op_sel_hi:[0,1]
	v_pk_mul_f32 v[36:37], v[102:103], v[40:41]
	v_pk_mul_f32 v[34:35], v[100:101], v[56:57]
	global_store_dwordx4 v[0:1], v[34:37], off offset:-3072 sc1 nt
	v_mov_b32_e32 v40, v55
	v_mov_b32_e32 v41, v39
	v_mov_b32_e32 v55, v38
	v_pk_mul_f32 v[38:39], v[52:53], v[40:41] op_sel_hi:[0,1]
	v_pk_mul_f32 v[40:41], v[52:53], v[54:55] op_sel_hi:[0,1]
	v_mov_b32_e32 v61, v68
	v_pk_mul_f32 v[34:35], v[104:105], v[40:41]
	v_pk_mul_f32 v[36:37], v[106:107], v[38:39]
	global_store_dwordx4 v[0:1], v[34:37], off offset:-2048 sc1 nt
	v_pk_mul_f32 v[38:39], v[64:65], v[52:53] op_sel_hi:[1,0]
	v_pk_mul_f32 v[40:41], v[58:59], v[52:53] op_sel_hi:[1,0]
	v_pk_mul_f32 v[36:37], v[110:111], v[38:39]
	v_pk_mul_f32 v[34:35], v[108:109], v[40:41]
	global_store_dwordx4 v[0:1], v[34:37], off offset:-1024 sc1 nt
	v_pk_mul_f32 v[38:39], v[66:67], v[52:53] op_sel_hi:[1,0]
	v_pk_mul_f32 v[40:41], v[60:61], v[52:53] op_sel_hi:[1,0]
	v_pk_mul_f32 v[36:37], v[114:115], v[38:39]
	v_pk_mul_f32 v[34:35], v[112:113], v[40:41]
	global_store_dwordx4 v[0:1], v[34:37], off sc1 nt
	s_cbranch_scc1 .LBB0_1699
	s_nop 0
	v_lshlrev_b32_e32 v35, 16, v33
	v_lshlrev_b32_e32 v34, 16, v32
	v_and_b32_e32 v33, 0xffff0000, v33
	v_and_b32_e32 v32, 0xffff0000, v32
	v_lshlrev_b32_e32 v39, 16, v31
	v_lshlrev_b32_e32 v38, 16, v30
	v_and_b32_e32 v31, 0xffff0000, v31
	v_and_b32_e32 v30, 0xffff0000, v30
	v_pk_mul_f32 v[36:37], v[32:33], v[32:33]
	v_pk_mul_f32 v[40:41], v[30:31], v[30:31]
	v_lshlrev_b32_e32 v50, 16, v28
	v_and_b32_e32 v51, 0xffff0000, v28
	v_lshlrev_b32_e32 v56, 16, v29
	v_lshlrev_b32_e32 v52, 16, v26
	v_pk_fma_f32 v[36:37], v[34:35], v[34:35], v[36:37]
	v_pk_fma_f32 v[40:41], v[38:39], v[38:39], v[40:41]
	v_mul_f32_e32 v53, v50, v50
	v_mul_f32_e32 v55, v51, v51
	v_and_b32_e32 v57, 0xffff0000, v29
	v_mul_f32_e32 v28, v56, v56
	v_mov_b32_e32 v54, v52
	v_pk_add_f32 v[36:37], v[36:37], v[36:37] op_sel_hi:[0,1]
	v_pk_add_f32 v[40:41], v[40:41], v[40:41] op_sel_hi:[0,1]
	v_pk_fma_f32 v[28:29], v[56:57], v[56:57], v[28:29] op_sel_hi:[1,1,0]
	v_and_b32_e32 v60, 0xffff0000, v26
	v_lshlrev_b32_e32 v58, 16, v27
	v_and_b32_e32 v59, 0xffff0000, v27
	v_pk_add_f32 v[54:55], v[52:53], v[54:55]
	v_mul_f32_e32 v28, v60, v60
	v_mul_f32_e32 v40, v58, v58
	v_mul_f32_e32 v36, v59, v59
	v_mul_f32_e32 v26, v52, v52
	v_mov_b32_e32 v27, v55
	v_pk_add_f32 v[26:27], v[26:27], v[28:29]
	v_pk_add_f32 v[28:29], v[40:41], v[36:37]
	s_ashr_i32 s7, s6, 31
	v_pk_add_f32 v[36:37], v[26:27], v[28:29]
	v_add_f32_e32 v36, v36, v37
	s_nop 1
	v_mov_b32_dpp v37, v36 quad_perm:[1,0,3,2] row_mask:0xf bank_mask:0xf
	s_waitcnt lgkmcnt(0)
	v_add_f32_e32 v36, v36, v37
	s_nop 1
	v_mov_b32_dpp v37, v36 quad_perm:[2,3,0,1] row_mask:0xf bank_mask:0xf
	s_waitcnt lgkmcnt(0)
	v_add_f32_e32 v36, v36, v37
	s_nop 1
	v_mov_b32_dpp v37, v36 row_half_mirror row_mask:0xf bank_mask:0xf
	s_waitcnt lgkmcnt(0)
	v_add_f32_e32 v36, v36, v37
	s_nop 1
	v_mov_b32_dpp v37, v36 row_mirror row_mask:0xf bank_mask:0xf
	s_waitcnt lgkmcnt(0)
	v_add_f32_e32 v36, v36, v37
	v_mov_b32_e32 v37, v36
	s_nop 1
	v_permlane16_swap_b32_e32 v36, v37
	s_waitcnt lgkmcnt(0)
	v_add_f32_e32 v36, v36, v37
	v_mov_b32_e32 v37, v36
	s_nop 1
	v_permlane32_swap_b32_e32 v36, v37
	s_waitcnt lgkmcnt(0)
	v_add_f32_e32 v36, v36, v37
	v_fmamk_f32 v36, v36, 0x3a800000, v48
	v_mul_f32_e32 v37, 0x4f800000, v36
	v_cmp_gt_f32_e32 vcc, s12, v36
	s_nop 1
	v_cndmask_b32_e32 v36, v36, v37, vcc
	v_sqrt_f32_e32 v37, v36
	s_nop 0
	v_add_u32_e32 v40, -1, v37
	v_fma_f32 v41, -v40, v37, v36
	v_cmp_ge_f32_e64 s[0:1], 0, v41
	v_add_u32_e32 v41, 1, v37
	s_nop 0
	v_cndmask_b32_e64 v40, v37, v40, s[0:1]
	v_fma_f32 v37, -v41, v37, v36
	v_cmp_lt_f32_e64 s[0:1], 0, v37
	s_nop 1
	v_cndmask_b32_e64 v37, v40, v41, s[0:1]
	v_mul_f32_e32 v40, 0x37800000, v37
	v_cndmask_b32_e32 v37, v37, v40, vcc
	v_cmp_class_f32_e32 vcc, v36, v49
	s_nop 1
	v_cndmask_b32_e32 v36, v37, v36, vcc
	v_div_scale_f32 v37, s[0:1], v36, v36, 1.0
	v_rcp_f32_e32 v40, v37
	s_lshl_b64 s[0:1], s[6:7], 12
	v_fma_f32 v41, -v37, v40, 1.0
	v_fmac_f32_e32 v40, v41, v40
	v_div_scale_f32 v41, vcc, 1.0, v36, 1.0
	v_mul_f32_e32 v53, v41, v40
	v_fma_f32 v54, -v37, v53, v41
	v_fmac_f32_e32 v53, v54, v40
	v_fma_f32 v37, -v37, v53, v41
	v_div_fmas_f32 v37, v37, v40, v53
	v_div_fixup_f32 v36, v37, v36, 1.0
	v_mov_b32_e32 v40, v34
	v_mov_b32_e32 v41, v32
	v_mov_b32_e32 v32, v35
	v_pk_mul_f32 v[40:41], v[36:37], v[40:41] op_sel_hi:[0,1]
	v_pk_mul_f32 v[32:33], v[36:37], v[32:33] op_sel_hi:[0,1]
	v_pk_mul_f32 v[28:29], v[102:103], v[32:33]
	v_pk_mul_f32 v[26:27], v[100:101], v[40:41]
	v_lshl_add_u64 v[32:33], v[6:7], 0, s[0:1]
	global_store_dwordx4 v[32:33], v[26:29], off sc1 nt
	v_mov_b32_e32 v34, v39
	v_mov_b32_e32 v35, v31
	v_mov_b32_e32 v39, v30
	v_pk_mul_f32 v[30:31], v[36:37], v[34:35] op_sel_hi:[0,1]
	v_pk_mul_f32 v[34:35], v[36:37], v[38:39] op_sel_hi:[0,1]
	v_mov_b32_e32 v53, v60
	v_pk_mul_f32 v[26:27], v[104:105], v[34:35]
	v_pk_mul_f32 v[28:29], v[106:107], v[30:31]
	global_store_dwordx4 v[32:33], v[26:29], off offset:1024 sc1 nt
	v_pk_mul_f32 v[30:31], v[56:57], v[36:37] op_sel_hi:[1,0]
	v_pk_mul_f32 v[34:35], v[50:51], v[36:37] op_sel_hi:[1,0]
	v_pk_mul_f32 v[28:29], v[110:111], v[30:31]
	v_pk_mul_f32 v[26:27], v[108:109], v[34:35]
	global_store_dwordx4 v[32:33], v[26:29], off offset:2048 sc1 nt
	v_pk_mul_f32 v[30:31], v[58:59], v[36:37] op_sel_hi:[1,0]
	v_pk_mul_f32 v[34:35], v[52:53], v[36:37] op_sel_hi:[1,0]
	v_pk_mul_f32 v[28:29], v[114:115], v[30:31]
	v_pk_mul_f32 v[26:27], v[112:113], v[34:35]
	global_store_dwordx4 v[32:33], v[26:29], off offset:3072 sc1 nt
	s_branch .LBB0_1699
